# mixers weight-transpose items: row loads of each unrolled iteration issued together (hipcc waited on every pair)
# baseline (speedup 1.0000x reference)
.LBB0_786:
	v_add_u32_e32 v24, s15, v8
	v_add_u32_e32 v26, s15, v9
	v_ashrrev_i32_e32 v25, 31, v24
	v_ashrrev_i32_e32 v27, 31, v26
	v_lshlrev_b64 v[28:29], 12, v[24:25]
	v_lshlrev_b64 v[24:25], 12, v[26:27]
	v_lshl_add_u64 v[26:27], v[6:7], 0, v[28:29]
	v_lshl_add_u64 v[28:29], v[6:7], 0, v[24:25]
	global_load_dword v24, v[26:27], off
	global_load_dword v25, v[28:29], off
	v_add_u32_e32 v26, s17, v8
	v_add_u32_e32 v28, s18, v9
	v_ashrrev_i32_e32 v27, 31, v26
	v_ashrrev_i32_e32 v29, 31, v28
	v_lshlrev_b64 v[30:31], 12, v[26:27]
	v_lshlrev_b64 v[26:27], 12, v[28:29]
	v_lshl_add_u64 v[28:29], v[6:7], 0, v[30:31]
	v_lshl_add_u64 v[30:31], v[6:7], 0, v[26:27]
	global_load_dword v26, v[28:29], off
	global_load_dword v27, v[30:31], off
	v_add_u32_e32 v28, s19, v8
	v_add_u32_e32 v30, s20, v9
	v_ashrrev_i32_e32 v29, 31, v28
	v_ashrrev_i32_e32 v31, 31, v30
	v_lshlrev_b64 v[32:33], 12, v[28:29]
	v_lshlrev_b64 v[28:29], 12, v[30:31]
	v_lshl_add_u64 v[30:31], v[6:7], 0, v[32:33]
	v_lshl_add_u64 v[32:33], v[6:7], 0, v[28:29]
	global_load_dword v28, v[30:31], off
	global_load_dword v29, v[32:33], off
	v_add_u32_e32 v30, s21, v8
	v_add_u32_e32 v32, s22, v9
	v_ashrrev_i32_e32 v31, 31, v30
	v_ashrrev_i32_e32 v33, 31, v32
	v_lshlrev_b64 v[34:35], 12, v[30:31]
	v_lshlrev_b64 v[30:31], 12, v[32:33]
	v_lshl_add_u64 v[32:33], v[6:7], 0, v[34:35]
	v_lshl_add_u64 v[34:35], v[6:7], 0, v[30:31]
	global_load_dword v30, v[32:33], off
	global_load_dword v31, v[34:35], off
	v_mad_u64_u32 v[14:15], s[0:1], v8, s75, v[4:5]
	v_mad_u64_u32 v[16:17], s[0:1], v9, s75, v[4:5]
	v_add_u32_e32 v12, -4, v12
	v_cmp_eq_u32_e64 s[0:1], 0, v12
	s_or_b64 s[10:11], s[0:1], s[10:11]
	s_waitcnt vmcnt(7)
	ds_write_b32 v14, v24
	s_waitcnt vmcnt(6)
	ds_write_b32 v16, v25
	s_waitcnt vmcnt(5)
	ds_write_b32 v14, v26 offset:2080
	s_waitcnt vmcnt(4)
	ds_write_b32 v16, v27 offset:2080
	v_add_u32_e32 v9, 32, v9
	v_add_u32_e32 v8, 32, v8
	s_waitcnt vmcnt(3)
	ds_write_b32 v14, v28 offset:4160
	s_waitcnt vmcnt(2)
	ds_write_b32 v16, v29 offset:4160
	s_waitcnt vmcnt(1)
	ds_write_b32 v14, v30 offset:6240
	s_waitcnt vmcnt(0)
	ds_write_b32 v16, v31 offset:6240
	s_andn2_b64 exec, exec, s[10:11]
	s_cbranch_execnz .LBB0_786
	s_or_b64 exec, exec, s[10:11]

.LBB0_813:
	v_add_u32_e32 v24, s15, v10
	v_add_u32_e32 v25, s15, v11
	v_mad_i64_i32 v[26:27], s[0:1], v24, s59, v[8:9]
	v_mad_i64_i32 v[28:29], s[0:1], v25, s59, v[8:9]
	global_load_dword v24, v[26:27], off
	global_load_dword v25, v[28:29], off
	v_add_u32_e32 v26, s17, v10
	v_add_u32_e32 v27, s18, v11
	v_mad_i64_i32 v[28:29], s[0:1], v26, s59, v[8:9]
	v_mad_i64_i32 v[30:31], s[0:1], v27, s59, v[8:9]
	global_load_dword v26, v[28:29], off
	global_load_dword v27, v[30:31], off
	v_mad_u64_u32 v[16:17], s[0:1], v10, s75, v[6:7]
	v_mad_u64_u32 v[18:19], s[0:1], v11, s75, v[6:7]
	v_add_u32_e32 v14, -2, v14
	s_waitcnt vmcnt(3)
	ds_write_b32 v16, v24
	s_waitcnt vmcnt(2)
	ds_write_b32 v18, v25
	v_cmp_eq_u32_e64 s[0:1], 0, v14
	v_add_u32_e32 v11, 16, v11
	v_add_u32_e32 v10, 16, v10
	s_or_b64 s[10:11], s[0:1], s[10:11]
	s_waitcnt vmcnt(1)
	ds_write_b32 v16, v26 offset:2080
	s_waitcnt vmcnt(0)
	ds_write_b32 v18, v27 offset:2080
	s_andn2_b64 exec, exec, s[10:11]
	s_cbranch_execnz .LBB0_813
	s_or_b64 exec, exec, s[10:11]

.LBB0_2272:
	v_add_u32_e32 v24, s15, v8
	v_add_u32_e32 v26, s15, v9
	v_ashrrev_i32_e32 v25, 31, v24
	v_ashrrev_i32_e32 v27, 31, v26
	v_lshlrev_b64 v[28:29], 12, v[24:25]
	v_lshlrev_b64 v[24:25], 12, v[26:27]
	v_lshl_add_u64 v[26:27], v[6:7], 0, v[28:29]
	v_lshl_add_u64 v[28:29], v[6:7], 0, v[24:25]
	global_load_dword v24, v[26:27], off
	global_load_dword v25, v[28:29], off
	v_add_u32_e32 v26, s16, v8
	v_add_u32_e32 v28, s17, v9
	v_ashrrev_i32_e32 v27, 31, v26
	v_ashrrev_i32_e32 v29, 31, v28
	v_lshlrev_b64 v[30:31], 12, v[26:27]
	v_lshlrev_b64 v[26:27], 12, v[28:29]
	v_lshl_add_u64 v[28:29], v[6:7], 0, v[30:31]
	v_lshl_add_u64 v[30:31], v[6:7], 0, v[26:27]
	global_load_dword v26, v[28:29], off
	global_load_dword v27, v[30:31], off
	v_add_u32_e32 v28, s18, v8
	v_add_u32_e32 v30, s19, v9
	v_ashrrev_i32_e32 v29, 31, v28
	v_ashrrev_i32_e32 v31, 31, v30
	v_lshlrev_b64 v[32:33], 12, v[28:29]
	v_lshlrev_b64 v[28:29], 12, v[30:31]
	v_lshl_add_u64 v[30:31], v[6:7], 0, v[32:33]
	v_lshl_add_u64 v[32:33], v[6:7], 0, v[28:29]
	global_load_dword v28, v[30:31], off
	global_load_dword v29, v[32:33], off
	v_add_u32_e32 v30, s20, v8
	v_add_u32_e32 v32, s21, v9
	v_ashrrev_i32_e32 v31, 31, v30
	v_ashrrev_i32_e32 v33, 31, v32
	v_lshlrev_b64 v[34:35], 12, v[30:31]
	v_lshlrev_b64 v[30:31], 12, v[32:33]
	v_lshl_add_u64 v[32:33], v[6:7], 0, v[34:35]
	v_lshl_add_u64 v[34:35], v[6:7], 0, v[30:31]
	global_load_dword v30, v[32:33], off
	global_load_dword v31, v[34:35], off
	v_mad_u64_u32 v[14:15], s[0:1], v8, s60, v[4:5]
	v_mad_u64_u32 v[16:17], s[0:1], v9, s60, v[4:5]
	v_add_u32_e32 v12, -4, v12
	v_cmp_eq_u32_e64 s[0:1], 0, v12
	s_or_b64 s[10:11], s[0:1], s[10:11]
	s_waitcnt vmcnt(7)
	ds_write_b32 v14, v24
	s_waitcnt vmcnt(6)
	ds_write_b32 v16, v25
	s_waitcnt vmcnt(5)
	ds_write_b32 v14, v26 offset:2080
	s_waitcnt vmcnt(4)
	ds_write_b32 v16, v27 offset:2080
	v_add_u32_e32 v9, 32, v9
	v_add_u32_e32 v8, 32, v8
	s_waitcnt vmcnt(3)
	ds_write_b32 v14, v28 offset:4160
	s_waitcnt vmcnt(2)
	ds_write_b32 v16, v29 offset:4160
	s_waitcnt vmcnt(1)
	ds_write_b32 v14, v30 offset:6240
	s_waitcnt vmcnt(0)
	ds_write_b32 v16, v31 offset:6240
	s_andn2_b64 exec, exec, s[10:11]
	s_cbranch_execnz .LBB0_2272
	s_or_b64 exec, exec, s[10:11]

.LBB0_2299:
	v_add_u32_e32 v24, s15, v10
	v_add_u32_e32 v25, s15, v11
	v_mad_i64_i32 v[26:27], s[0:1], v24, s62, v[8:9]
	v_mad_i64_i32 v[28:29], s[0:1], v25, s62, v[8:9]
	global_load_dword v24, v[26:27], off
	global_load_dword v25, v[28:29], off
	v_add_u32_e32 v26, s16, v10
	v_add_u32_e32 v27, s17, v11
	v_mad_i64_i32 v[28:29], s[0:1], v26, s62, v[8:9]
	v_mad_i64_i32 v[30:31], s[0:1], v27, s62, v[8:9]
	global_load_dword v26, v[28:29], off
	global_load_dword v27, v[30:31], off
	v_mad_u64_u32 v[16:17], s[0:1], v10, s60, v[6:7]
	v_mad_u64_u32 v[18:19], s[0:1], v11, s60, v[6:7]
	v_add_u32_e32 v14, -2, v14
	s_waitcnt vmcnt(3)
	ds_write_b32 v16, v24
	s_waitcnt vmcnt(2)
	ds_write_b32 v18, v25
	v_cmp_eq_u32_e64 s[0:1], 0, v14
	v_add_u32_e32 v11, 16, v11
	v_add_u32_e32 v10, 16, v10
	s_or_b64 s[10:11], s[0:1], s[10:11]
	s_waitcnt vmcnt(1)
	ds_write_b32 v16, v26 offset:2080
	s_waitcnt vmcnt(0)
	ds_write_b32 v18, v27 offset:2080
	s_andn2_b64 exec, exec, s[10:11]
	s_cbranch_execnz .LBB0_2299
	s_or_b64 exec, exec, s[10:11]
